# strategy 5: GLA scan item rewritten by hand, LDS-DMA staging with two batches in flight
# speedup vs baseline: 1.0059x; 1.0021x over previous
; DI unsigned pk2(float lo, float hi) { return pg8::cvt_pk_bf16(lo, hi); }
; DI f32x4 mfma16(bf16x8 a, bf16x8 b, f32x4 c) { return __builtin_amdgcn_mfma_f32_16x16x32_bf16(a, b, c, 0, 0, 0); }
; #define WSP() ((unsigned char*)karg(168))
; DI void gla_scan_item_lds(unsigned char* ldsb, int item, int tid, int wave, int lane) {
;     unsigned char* R = WSP() + WS_R; bf16* SBEF = (bf16*)(R + R_SBEF);
;     const int es = item & 3, chain = item >> 2, dir = chain >> 5;
;     const int c = lane & 15, g = lane >> 4, ebl = wave >> 2, db = wave & 3, e0 = 32 * es + 16 * ebl;
;     bf16* sp = SBEF + ((size_t)chain * 64 * 128 + e0 + c) * 64 + 16 * db + 4 * g;
;     const int ao = g * 1024 + (16 * db + c) * 16, bo = 8192 + g * 512 + (16 * ebl + c) * 16, dco = 12288 + (16 * db + 4 * g) * 4;
;     f32x4 S = {0.f, 0.f, 0.f, 0.f};
;     ScStage st; sc_gload(st, item, 0, tid); sc_lwrite(st, ldsb, tid); sc_gload(st, item, 1, tid);
;     __syncthreads();
; #pragma unroll 1
;     for (int m = 0; m < 16; ++m) {
;         const unsigned char* buf = ldsb + (m & 1) * SC_BATCH_B;
; #pragma unroll
;         for (int s4 = 0; s4 < 4; ++s4) {
;             const int n = 4 * m + s4, cc = dir ? 63 - n : n; const unsigned char* sb = buf + s4 * SC_STEP_B;
;             u32x2 w_; w_.x = pk2(S[0], S[1]); w_.y = pk2(S[2], S[3]); *(u32x2*)(sp + (size_t)cc * 128 * 64) = w_;
;             const f32x4 dc = *(const f32x4*)(sb + dco);
;             S = S * dc;
;             S = mfma16(*(const bf16x8*)(sb + ao), *(const bf16x8*)(sb + bo), S);
;             S = mfma16(*(const bf16x8*)(sb + ao + 4096), *(const bf16x8*)(sb + bo + 2048), S);
;         }
.LBB0_669:
	s_lshl_b32 s3, s29, 3
	s_and_b32 s3, s3, 0xffffff80
	v_readlane_b32 s8, v245, 9
	s_or_b32 s3, s3, s8
	s_and_b32 s8, s29, 15
	s_or_b32 s3, s3, s8
	s_and_b64 s[12:13], s[6:7], exec
	s_movk_i32 s8, 0xa8
	s_cselect_b32 s3, s3, s29
	s_and_b32 s8, s3, 3
	s_lshr_b32 s12, s3, 2
	s_lshr_b32 s13, s12, 5
	s_and_b32 s14, s12, 31
	s_and_b32 s15, s14, 3
	s_lshr_b32 s14, s14, 2
	s_load_dwordx2 s[50:51], s[0:1], 0xa8
	v_lshrrev_b32_e32 v8, 6, v165
	v_and_b32_e32 v14, 63, v165
	v_readfirstlane_b32 s22, v8
	s_waitcnt lgkmcnt(0)
	s_add_u32 s38, s50, 0x1d600000
	s_addc_u32 s39, s51, 0
	s_lshl_b32 s3, s14, 22
	s_add_u32 s38, s38, s3
	s_addc_u32 s39, s39, 0
	s_lshl_b32 s3, s13, 12
	s_add_u32 s38, s38, s3
	s_addc_u32 s39, s39, 0
	s_lshl_b32 s3, s15, 10
	s_add_u32 s38, s38, s3
	s_addc_u32 s39, s39, 0
	s_lshl_b32 s3, s22, 13
	s_add_u32 s38, s38, s3
	s_addc_u32 s39, s39, 0
	s_add_u32 s40, s50, 0xd602000
	s_addc_u32 s41, s51, 0
	s_lshl_b32 s3, s14, 23
	s_add_u32 s40, s40, s3
	s_addc_u32 s41, s41, 0
	s_lshl_b32 s3, s15, 11
	s_add_u32 s40, s40, s3
	s_addc_u32 s41, s41, 0
	s_lshl_b32 s3, s8, 9
	s_add_u32 s40, s40, s3
	s_addc_u32 s41, s41, 0
	s_lshl_b32 s3, s22, 15
	s_add_u32 s40, s40, s3
	s_addc_u32 s41, s41, 0
	s_add_u32 s44, s50, 0x1f800000
	s_addc_u32 s45, s51, 0
	s_lshl_b32 s3, s12, 14
	s_add_u32 s44, s44, s3
	s_addc_u32 s45, s45, 0
	s_add_u32 s46, s50, 0x17600000
	s_addc_u32 s47, s51, 0
	s_lshl_b32 s3, s12, 20
	s_add_u32 s46, s46, s3
	s_addc_u32 s47, s47, 0
	v_lshlrev_b32_e32 v2, 4, v14
	v_lshrrev_b32_e32 v3, 5, v14
	v_lshlrev_b32_e32 v3, 14, v3
	v_and_b32_e32 v4, 31, v14
	v_lshl_or_b32 v3, v4, 4, v3
	v_and_b32_e32 v9, 15, v14
	v_lshrrev_b32_e32 v10, 4, v14
	s_and_b32 s48, s22, 3
	s_lshr_b32 s49, s22, 2
	s_lshl_b32 s3, s48, 8
	v_lshl_add_u32 v5, v10, 10, s3
	v_lshl_add_u32 v5, v9, 4, v5
	s_lshl_b32 s3, s49, 8
	s_add_i32 s3, s3, 8192
	v_lshl_add_u32 v6, v10, 9, s3
	v_lshl_add_u32 v6, v9, 4, v6
	s_lshl_b32 s3, s48, 6
	s_add_i32 s3, s3, 12288
	v_lshl_add_u32 v7, v10, 4, s3
	s_lshl_b32 s3, s8, 12
	s_lshl_b32 s50, s49, 11
	s_add_i32 s3, s3, s50
	s_lshl_b32 s50, s48, 5
	s_add_i32 s3, s3, s50
	v_lshl_add_u32 v4, v9, 7, s3
	v_lshl_add_u32 v4, v10, 3, v4
	v_mov_b32_e32 v34, 0
	v_mov_b32_e32 v35, 0
	v_mov_b32_e32 v36, 0
	v_mov_b32_e32 v37, 0
	s_mov_b32 s30, 0
.Lsc_loop:
	s_cmp_lt_u32 s30, 2
	s_cbranch_scc1 .Lsc_dma
	s_cmp_lt_u32 s22, 5
	s_cbranch_scc0 .Lsc_w4
	s_waitcnt vmcnt(12)
	s_branch .Lsc_w
.Lsc_w4:
	s_waitcnt vmcnt(8)
.Lsc_w:
	s_cmp_eq_u32 s30, 2
	s_cbranch_scc1 .Lsc_strict
	s_cmp_eq_u32 s30, 17
	s_cbranch_scc0 .Lsc_go
.Lsc_strict:
	s_waitcnt vmcnt(4)
.Lsc_go:
	s_barrier
	s_and_b32 s48, s30, 1
	s_mul_i32 s48, s48, 0xc400
	v_add_u32_e32 v11, s48, v5
	v_add_u32_e32 v12, s48, v6
	v_add_u32_e32 v13, s48, v7
	ds_read_b128 v[68:71], v13
	ds_read_b128 v[72:75], v11
	ds_read_b128 v[76:79], v12
	ds_read_b128 v[80:83], v11 offset:4096
	ds_read_b128 v[84:87], v12 offset:2048
	ds_read_b128 v[88:91], v13 offset:12544
	ds_read_b128 v[92:95], v11 offset:12544
	ds_read_b128 v[96:99], v12 offset:12544
	ds_read_b128 v[100:103], v11 offset:16640
	ds_read_b128 v[104:107], v12 offset:14592
	ds_read_b128 v[108:111], v13 offset:25088
	ds_read_b128 v[112:115], v11 offset:25088
	ds_read_b128 v[116:119], v12 offset:25088
	ds_read_b128 v[120:123], v11 offset:29184
	ds_read_b128 v[124:127], v12 offset:27136
	ds_read_b128 v[128:131], v13 offset:37632
	ds_read_b128 v[132:135], v11 offset:37632
	ds_read_b128 v[136:139], v12 offset:37632
	ds_read_b128 v[140:143], v11 offset:41728
	ds_read_b128 v[144:147], v12 offset:39680
	s_waitcnt lgkmcnt(0)
	s_barrier
	s_sub_i32 s53, s30, 2
	s_lshl_b32 s53, s53, 2
	s_add_i32 s52, s53, 0
	s_sub_i32 s49, 63, s52
	s_cmp_lg_u32 s13, 0
	s_cselect_b32 s52, s49, s52
	s_lshl_b32 s52, s52, 14
	s_add_u32 s50, s46, s52
	s_addc_u32 s51, s47, 0
	v_cvt_pk_bf16_f32 v50, v34, v35
	v_cvt_pk_bf16_f32 v51, v36, v37
	global_store_dwordx2 v4, v[50:51], s[50:51]
	v_pk_mul_f32 v[36:37], v[36:37], v[70:71]
	v_pk_mul_f32 v[34:35], v[34:35], v[68:69]
	s_nop 1
	v_mfma_f32_16x16x32_bf16 v[34:37], v[72:75], v[76:79], v[34:37]
	v_mfma_f32_16x16x32_bf16 v[34:37], v[80:83], v[84:87], v[34:37]
	s_add_i32 s52, s53, 1
	s_sub_i32 s49, 63, s52
	s_cmp_lg_u32 s13, 0
	s_cselect_b32 s52, s49, s52
	s_lshl_b32 s52, s52, 14
	s_add_u32 s50, s46, s52
	s_addc_u32 s51, s47, 0
	s_nop 2
	v_cvt_pk_bf16_f32 v50, v34, v35
	v_cvt_pk_bf16_f32 v51, v36, v37
	global_store_dwordx2 v4, v[50:51], s[50:51]
	v_pk_mul_f32 v[36:37], v[36:37], v[90:91]
	v_pk_mul_f32 v[34:35], v[34:35], v[88:89]
	s_nop 1
	v_mfma_f32_16x16x32_bf16 v[34:37], v[92:95], v[96:99], v[34:37]
	v_mfma_f32_16x16x32_bf16 v[34:37], v[100:103], v[104:107], v[34:37]
	s_add_i32 s52, s53, 2
	s_sub_i32 s49, 63, s52
	s_cmp_lg_u32 s13, 0
	s_cselect_b32 s52, s49, s52
	s_lshl_b32 s52, s52, 14
	s_add_u32 s50, s46, s52
	s_addc_u32 s51, s47, 0
	s_nop 2
	v_cvt_pk_bf16_f32 v50, v34, v35
	v_cvt_pk_bf16_f32 v51, v36, v37
	global_store_dwordx2 v4, v[50:51], s[50:51]
	v_pk_mul_f32 v[36:37], v[36:37], v[110:111]
	v_pk_mul_f32 v[34:35], v[34:35], v[108:109]
	s_nop 1
	v_mfma_f32_16x16x32_bf16 v[34:37], v[112:115], v[116:119], v[34:37]
	v_mfma_f32_16x16x32_bf16 v[34:37], v[120:123], v[124:127], v[34:37]
	s_add_i32 s52, s53, 3
	s_sub_i32 s49, 63, s52
	s_cmp_lg_u32 s13, 0
	s_cselect_b32 s52, s49, s52
	s_lshl_b32 s52, s52, 14
	s_add_u32 s50, s46, s52
	s_addc_u32 s51, s47, 0
	s_nop 2
	v_cvt_pk_bf16_f32 v50, v34, v35
	v_cvt_pk_bf16_f32 v51, v36, v37
	global_store_dwordx2 v4, v[50:51], s[50:51]
	v_pk_mul_f32 v[36:37], v[36:37], v[130:131]
	v_pk_mul_f32 v[34:35], v[34:35], v[128:129]
	s_nop 1
	v_mfma_f32_16x16x32_bf16 v[34:37], v[132:135], v[136:139], v[34:37]
	v_mfma_f32_16x16x32_bf16 v[34:37], v[140:143], v[144:147], v[34:37]
; #define WSP() ((unsigned char*)karg(168))
; DI void sc_gload(ScStage& st, int item, int batch, int tid) {
;     unsigned char* R = WSP() + WS_R;
;     const bf16* VT = (const bf16*)(R + R_VT); const bf16* KT = (const bf16*)(R + R_KT); const float* DEC = (const float*)(R + R_DEC);
;     const int es = item & 3, chain = item >> 2, dir = chain >> 5, bh = chain & 31, h = bh & 3, b = bh >> 2;
; #pragma unroll
;     for (int s4 = 0; s4 < 4; ++s4) {
;         const int n = 4 * batch + s4, cc = dir ? 63 - n : n;
;         st.k[s4] = *(const u32x4*)(KT + ((size_t)(b * 512 + cc * 8 + (tid >> 6)) * 512 + dir * 256 + h * 64 + (tid & 63)) * 8);
;         if (tid < 256) st.x[s4] = *(const u32x4*)(VT + ((size_t)(b * 512 + cc * 8 + (tid >> 5)) * 1024 + 512 + h * 128 + 32 * es + (tid & 31)) * 8);
;         else if (tid < 272) st.x[s4] = *(const u32x4*)(DEC + ((size_t)chain * 64 + cc) * 64 + (tid - 256) * 4);
;     }
; }
; DI void sc_lwrite(const ScStage& st, unsigned char* buf, int tid) {
; #pragma unroll
;     for (int s4 = 0; s4 < 4; ++s4) {
;         *(u32x4*)(buf + s4 * SC_STEP_B + tid * 16) = st.k[s4];
;         if (tid < 256) *(u32x4*)(buf + s4 * SC_STEP_B + 8192 + tid * 16) = st.x[s4];
;         else if (tid < 272) *(u32x4*)(buf + s4 * SC_STEP_B + 12288 + (tid - 256) * 16) = st.x[s4];
;     }
; }
; DI void gla_scan_item_lds(unsigned char* ldsb, int item, int tid, int wave, int lane) {
;     ...
;         if (m < 15) sc_lwrite(st, ldsb + ((m + 1) & 1) * SC_BATCH_B, tid);
;         if (m < 14) sc_gload(st, item, m + 2, tid);
;         __syncthreads();
;     }
.Lsc_dma:
	s_cmp_gt_u32 s30, 15
	s_cbranch_scc1 .Lsc_next
	s_and_b32 s48, s30, 1
	s_mul_i32 s48, s48, 0xc400
	s_lshl_b32 s49, s22, 10
	s_add_i32 s48, s48, s49
	s_lshl_b32 s53, s30, 2
	s_add_i32 s52, s53, 0
	s_sub_i32 s49, 63, s52
	s_cmp_lg_u32 s13, 0
	s_cselect_b32 s52, s49, s52
	s_lshl_b32 s49, s52, 16
	s_add_u32 s50, s38, s49
	s_addc_u32 s51, s39, 0
	s_add_i32 m0, s48, 0
	s_nop 0
	global_load_lds_dwordx4 v2, s[50:51]
	s_add_i32 s52, s53, 1
	s_sub_i32 s49, 63, s52
	s_cmp_lg_u32 s13, 0
	s_cselect_b32 s52, s49, s52
	s_lshl_b32 s49, s52, 16
	s_add_u32 s50, s38, s49
	s_addc_u32 s51, s39, 0
	s_add_i32 m0, s48, 12544
	s_nop 0
	global_load_lds_dwordx4 v2, s[50:51]
	s_add_i32 s52, s53, 2
	s_sub_i32 s49, 63, s52
	s_cmp_lg_u32 s13, 0
	s_cselect_b32 s52, s49, s52
	s_lshl_b32 s49, s52, 16
	s_add_u32 s50, s38, s49
	s_addc_u32 s51, s39, 0
	s_add_i32 m0, s48, 25088
	s_nop 0
	global_load_lds_dwordx4 v2, s[50:51]
	s_add_i32 s52, s53, 3
	s_sub_i32 s49, 63, s52
	s_cmp_lg_u32 s13, 0
	s_cselect_b32 s52, s49, s52
	s_lshl_b32 s49, s52, 16
	s_add_u32 s50, s38, s49
	s_addc_u32 s51, s39, 0
	s_add_i32 m0, s48, 37632
	s_nop 0
	global_load_lds_dwordx4 v2, s[50:51]
	s_cmp_lt_u32 s22, 4
	s_cbranch_scc0 .Lsc_nox
	s_add_i32 s52, s53, 0
	s_sub_i32 s49, 63, s52
	s_cmp_lg_u32 s13, 0
	s_cselect_b32 s52, s49, s52
	s_lshl_b32 s49, s52, 17
	s_add_u32 s50, s40, s49
	s_addc_u32 s51, s41, 0
	s_add_i32 m0, s48, 8192
	s_nop 0
	global_load_lds_dwordx4 v3, s[50:51]
	s_add_i32 s52, s53, 1
	s_sub_i32 s49, 63, s52
	s_cmp_lg_u32 s13, 0
	s_cselect_b32 s52, s49, s52
	s_lshl_b32 s49, s52, 17
	s_add_u32 s50, s40, s49
	s_addc_u32 s51, s41, 0
	s_add_i32 m0, s48, 20736
	s_nop 0
	global_load_lds_dwordx4 v3, s[50:51]
	s_add_i32 s52, s53, 2
	s_sub_i32 s49, 63, s52
	s_cmp_lg_u32 s13, 0
	s_cselect_b32 s52, s49, s52
	s_lshl_b32 s49, s52, 17
	s_add_u32 s50, s40, s49
	s_addc_u32 s51, s41, 0
	s_add_i32 m0, s48, 33280
	s_nop 0
	global_load_lds_dwordx4 v3, s[50:51]
	s_add_i32 s52, s53, 3
	s_sub_i32 s49, 63, s52
	s_cmp_lg_u32 s13, 0
	s_cselect_b32 s52, s49, s52
	s_lshl_b32 s49, s52, 17
	s_add_u32 s50, s40, s49
	s_addc_u32 s51, s41, 0
	s_add_i32 m0, s48, 45824
	s_nop 0
	global_load_lds_dwordx4 v3, s[50:51]
	s_branch .Lsc_next
.Lsc_nox:
	s_cmp_eq_u32 s22, 4
	s_cbranch_scc0 .Lsc_next
	s_and_b32 s48, s30, 1
	s_mul_i32 s48, s48, 0xc400
	s_mov_b64 exec, 0xffff
	s_add_i32 s52, s53, 0
	s_sub_i32 s49, 63, s52
	s_cmp_lg_u32 s13, 0
	s_cselect_b32 s52, s49, s52
	s_lshl_b32 s49, s52, 8
	s_add_u32 s50, s44, s49
	s_addc_u32 s51, s45, 0
	s_add_i32 m0, s48, 12288
	s_nop 0
	global_load_lds_dwordx4 v2, s[50:51]
	s_add_i32 s52, s53, 1
	s_sub_i32 s49, 63, s52
	s_cmp_lg_u32 s13, 0
	s_cselect_b32 s52, s49, s52
	s_lshl_b32 s49, s52, 8
	s_add_u32 s50, s44, s49
	s_addc_u32 s51, s45, 0
	s_add_i32 m0, s48, 24832
	s_nop 0
	global_load_lds_dwordx4 v2, s[50:51]
	s_add_i32 s52, s53, 2
	s_sub_i32 s49, 63, s52
	s_cmp_lg_u32 s13, 0
	s_cselect_b32 s52, s49, s52
	s_lshl_b32 s49, s52, 8
	s_add_u32 s50, s44, s49
	s_addc_u32 s51, s45, 0
	s_add_i32 m0, s48, 37376
	s_nop 0
	global_load_lds_dwordx4 v2, s[50:51]
	s_add_i32 s52, s53, 3
	s_sub_i32 s49, 63, s52
	s_cmp_lg_u32 s13, 0
	s_cselect_b32 s52, s49, s52
	s_lshl_b32 s49, s52, 8
	s_add_u32 s50, s44, s49
	s_addc_u32 s51, s45, 0
	s_add_i32 m0, s48, 49920
	s_nop 0
	global_load_lds_dwordx4 v2, s[50:51]
	s_mov_b64 exec, -1
.Lsc_next:
	s_add_i32 s30, s30, 1
	s_cmp_lt_u32 s30, 18
	s_cbranch_scc1 .Lsc_loop
	s_branch .LBB0_668
